# S5 rstd table loads all in flight; work-queue draw prefetched one round ahead; conv fix-up tap loads batched
# speedup vs baseline: 1.0175x; 1.0004x over previous
; __device__ __forceinline__ float rstd_of(float ssq) { return __builtin_amdgcn_rsqf(ssq * (1.0f / DM) + RMS_EPS); }
; __device__ __forceinline__ float row_ssq(const float* part, int row, int np4) { const f32x4* p = (const f32x4*)(part + (size_t)row * 64); f32x4 a = p[0];
; #pragma unroll 8
;     for (int j = 1; j < np4; ++j) a += p[j];
;     return (a[0] + a[1]) + (a[2] + a[3]); }
; __device__ __forceinline__ void s5_phase(const bf16_t* __restrict__ HN, bf16_t* __restrict__ Y, const float* __restrict__ rsq, const float* __restrict__ gmix, const float* lam_re, const float* lam_im, const float* log_step, ...
;     ...
;         const int pr = pr0 + hf, b = pr / SSM_G, g = pr % SSM_G;
;         for (int t = tid; t < SEQ; t += NTHR) RT[t] = rstd_of(row_ssq(rsq, b * SEQ + t, 8));
.LBB0_168:
	s_or_b32 s2, s46, s18
	s_ashr_i32 s3, s2, 31
	s_lshr_b32 s3, s3, 25
	s_add_i32 s3, s2, s3
	s_ashr_i32 s3, s3, 7
	s_lshl_b32 s72, s3, 11
	s_and_saveexec_b64 s[6:7], s[4:5]
	s_cbranch_execz .LBB0_171
	v_add_u32_e32 v0, s72, v61
	v_ashrrev_i32_e32 v1, 31, v0
	v_lshlrev_b64 v[0:1], 8, v[0:1]
	s_mov_b64 s[34:35], s[64:65]
	v_lshl_add_u64 v[2:3], s[34:35], 0, v[0:1]
	global_load_dwordx4 v[8:11], v[2:3], off
	global_load_dwordx4 v[12:15], v[2:3], off offset:16
	global_load_dwordx4 v[16:19], v[2:3], off offset:32
	global_load_dwordx4 v[20:23], v[2:3], off offset:48
	global_load_dwordx4 v[24:27], v[2:3], off offset:64
	global_load_dwordx4 v[28:31], v[2:3], off offset:80
	global_load_dwordx4 v[32:35], v[2:3], off offset:96
	global_load_dwordx4 v[36:39], v[2:3], off offset:112
	s_add_u32 s34, s34, 0x20000
	s_addc_u32 s35, s35, 0
	v_lshl_add_u64 v[2:3], s[34:35], 0, v[0:1]
	global_load_dwordx4 v[40:43], v[2:3], off
	global_load_dwordx4 v[44:47], v[2:3], off offset:16
	global_load_dwordx4 v[48:51], v[2:3], off offset:32
	global_load_dwordx4 v[52:55], v[2:3], off offset:48
	global_load_dwordx4 v[56:59], v[2:3], off offset:64
	global_load_dwordx4 v[112:115], v[2:3], off offset:80
	global_load_dwordx4 v[116:119], v[2:3], off offset:96
	global_load_dwordx4 v[120:123], v[2:3], off offset:112
	s_add_u32 s34, s34, 0x20000
	s_addc_u32 s35, s35, 0
	v_lshl_add_u64 v[2:3], s[34:35], 0, v[0:1]
	global_load_dwordx4 v[124:127], v[2:3], off
	global_load_dwordx4 v[128:131], v[2:3], off offset:16
	global_load_dwordx4 v[132:135], v[2:3], off offset:32
	global_load_dwordx4 v[172:175], v[2:3], off offset:48
	global_load_dwordx4 v[176:179], v[2:3], off offset:64
	global_load_dwordx4 v[180:183], v[2:3], off offset:80
	global_load_dwordx4 v[184:187], v[2:3], off offset:96
	global_load_dwordx4 v[188:191], v[2:3], off offset:112
	s_add_u32 s34, s34, 0x20000
	s_addc_u32 s35, s35, 0
	v_lshl_add_u64 v[2:3], s[34:35], 0, v[0:1]
	global_load_dwordx4 v[192:195], v[2:3], off
	global_load_dwordx4 v[196:199], v[2:3], off offset:16
	global_load_dwordx4 v[200:203], v[2:3], off offset:32
	global_load_dwordx4 v[212:215], v[2:3], off offset:48
	global_load_dwordx4 v[216:219], v[2:3], off offset:64
	global_load_dwordx4 v[220:223], v[2:3], off offset:80
	global_load_dwordx4 v[224:227], v[2:3], off offset:96
	global_load_dwordx4 v[228:231], v[2:3], off offset:112
	s_waitcnt vmcnt(24)
	v_add_f32_e32 v8, v8, v12
	v_add_f32_e32 v9, v9, v13
	v_add_f32_e32 v10, v10, v14
	v_add_f32_e32 v11, v11, v15
	v_add_f32_e32 v8, v8, v16
	v_add_f32_e32 v9, v9, v17
	v_add_f32_e32 v10, v10, v18
	v_add_f32_e32 v11, v11, v19
	v_add_f32_e32 v8, v8, v20
	v_add_f32_e32 v9, v9, v21
	v_add_f32_e32 v10, v10, v22
	v_add_f32_e32 v11, v11, v23
	v_add_f32_e32 v8, v8, v24
	v_add_f32_e32 v9, v9, v25
	v_add_f32_e32 v10, v10, v26
	v_add_f32_e32 v11, v11, v27
	v_add_f32_e32 v8, v8, v28
	v_add_f32_e32 v9, v9, v29
	v_add_f32_e32 v10, v10, v30
	v_add_f32_e32 v11, v11, v31
	v_add_f32_e32 v8, v8, v32
	v_add_f32_e32 v9, v9, v33
	v_add_f32_e32 v10, v10, v34
	v_add_f32_e32 v11, v11, v35
	v_add_f32_e32 v8, v8, v36
	v_add_f32_e32 v9, v9, v37
	v_add_f32_e32 v10, v10, v38
	v_add_f32_e32 v11, v11, v39
	v_add_f32_e32 v8, v9, v8
	v_add_f32_e32 v10, v10, v11
	v_add_f32_e32 v8, v8, v10
	v_fmamk_f32 v8, v8, 0x3a000000, v243
	v_rsq_f32_e32 v8, v8
	s_nop 0
	ds_write_b32 v167, v8
	s_waitcnt vmcnt(16)
	v_add_f32_e32 v40, v40, v44
	v_add_f32_e32 v41, v41, v45
	v_add_f32_e32 v42, v42, v46
	v_add_f32_e32 v43, v43, v47
	v_add_f32_e32 v40, v40, v48
	v_add_f32_e32 v41, v41, v49
	v_add_f32_e32 v42, v42, v50
	v_add_f32_e32 v43, v43, v51
	v_add_f32_e32 v40, v40, v52
	v_add_f32_e32 v41, v41, v53
	v_add_f32_e32 v42, v42, v54
	v_add_f32_e32 v43, v43, v55
	v_add_f32_e32 v40, v40, v56
	v_add_f32_e32 v41, v41, v57
	v_add_f32_e32 v42, v42, v58
	v_add_f32_e32 v43, v43, v59
	v_add_f32_e32 v40, v40, v112
	v_add_f32_e32 v41, v41, v113
	v_add_f32_e32 v42, v42, v114
	v_add_f32_e32 v43, v43, v115
	v_add_f32_e32 v40, v40, v116
	v_add_f32_e32 v41, v41, v117
	v_add_f32_e32 v42, v42, v118
	v_add_f32_e32 v43, v43, v119
	v_add_f32_e32 v40, v40, v120
	v_add_f32_e32 v41, v41, v121
	v_add_f32_e32 v42, v42, v122
	v_add_f32_e32 v43, v43, v123
	v_add_f32_e32 v40, v41, v40
	v_add_f32_e32 v42, v42, v43
	v_add_f32_e32 v40, v40, v42
	v_fmamk_f32 v40, v40, 0x3a000000, v243
	v_rsq_f32_e32 v40, v40
	s_nop 0
	ds_write_b32 v167, v40 offset:2048
	s_waitcnt vmcnt(8)
	v_add_f32_e32 v124, v124, v128
	v_add_f32_e32 v125, v125, v129
	v_add_f32_e32 v126, v126, v130
	v_add_f32_e32 v127, v127, v131
	v_add_f32_e32 v124, v124, v132
	v_add_f32_e32 v125, v125, v133
	v_add_f32_e32 v126, v126, v134
	v_add_f32_e32 v127, v127, v135
	v_add_f32_e32 v124, v124, v172
	v_add_f32_e32 v125, v125, v173
	v_add_f32_e32 v126, v126, v174
	v_add_f32_e32 v127, v127, v175
	v_add_f32_e32 v124, v124, v176
	v_add_f32_e32 v125, v125, v177
	v_add_f32_e32 v126, v126, v178
	v_add_f32_e32 v127, v127, v179
	v_add_f32_e32 v124, v124, v180
	v_add_f32_e32 v125, v125, v181
	v_add_f32_e32 v126, v126, v182
	v_add_f32_e32 v127, v127, v183
	v_add_f32_e32 v124, v124, v184
	v_add_f32_e32 v125, v125, v185
	v_add_f32_e32 v126, v126, v186
	v_add_f32_e32 v127, v127, v187
	v_add_f32_e32 v124, v124, v188
	v_add_f32_e32 v125, v125, v189
	v_add_f32_e32 v126, v126, v190
	v_add_f32_e32 v127, v127, v191
	v_add_f32_e32 v124, v125, v124
	v_add_f32_e32 v126, v126, v127
	v_add_f32_e32 v124, v124, v126
	v_fmamk_f32 v124, v124, 0x3a000000, v243
	v_rsq_f32_e32 v124, v124
	s_nop 0
	ds_write_b32 v167, v124 offset:4096
	s_waitcnt vmcnt(0)
	v_add_f32_e32 v192, v192, v196
	v_add_f32_e32 v193, v193, v197
	v_add_f32_e32 v194, v194, v198
	v_add_f32_e32 v195, v195, v199
	v_add_f32_e32 v192, v192, v200
	v_add_f32_e32 v193, v193, v201
	v_add_f32_e32 v194, v194, v202
	v_add_f32_e32 v195, v195, v203
	v_add_f32_e32 v192, v192, v212
	v_add_f32_e32 v193, v193, v213
	v_add_f32_e32 v194, v194, v214
	v_add_f32_e32 v195, v195, v215
	v_add_f32_e32 v192, v192, v216
	v_add_f32_e32 v193, v193, v217
	v_add_f32_e32 v194, v194, v218
	v_add_f32_e32 v195, v195, v219
	v_add_f32_e32 v192, v192, v220
	v_add_f32_e32 v193, v193, v221
	v_add_f32_e32 v194, v194, v222
	v_add_f32_e32 v195, v195, v223
	v_add_f32_e32 v192, v192, v224
	v_add_f32_e32 v193, v193, v225
	v_add_f32_e32 v194, v194, v226
	v_add_f32_e32 v195, v195, v227
	v_add_f32_e32 v192, v192, v228
	v_add_f32_e32 v193, v193, v229
	v_add_f32_e32 v194, v194, v230
	v_add_f32_e32 v195, v195, v231
	v_add_f32_e32 v192, v193, v192
	v_add_f32_e32 v194, v194, v195
	v_add_f32_e32 v192, v192, v194
	v_fmamk_f32 v192, v192, 0x3a000000, v243
	v_rsq_f32_e32 v192, v192
	s_nop 0
	ds_write_b32 v167, v192 offset:6144

; #define LAS __attribute__((address_space(3)))
; __device__ __forceinline__ void convert_layer(int lc, unsigned* ctr, LAS unsigned char* lds, int tid, int wid, int lane) {
;     const int l = lc + 1, kind = (l < DEPTH) ? l % 3 : 0;
;     const int nmix = (kind == 1) ? (32 * 96 + 32 * 32) : (kind == 2) ? (32 * 64) : 0;
;     const int total = DN_ITEMS + ((l < DEPTH) ? nmix + UP_ITEMS : 0);
;     LAS float* scr = (LAS float*)(lds + wid * (64 * 65 * 4));
;     volatile LAS unsigned* slot = (volatile LAS unsigned*)(lds + LDS_BYTES - 8);
;     for (;;) {
;         if (tid == 0) *slot = __hip_atomic_fetch_add(ctr, 16u, __ATOMIC_RELAXED, __HIP_MEMORY_SCOPE_AGENT);
;         __syncthreads();
;         const int base = (int)*slot;
;         __syncthreads();
;         if (base >= total) break;
.LBB0_1121:
	s_mov_b32 s2, s19
	s_ashr_i32 s3, s2, 31
	s_lshl_b64 s[2:3], s[2:3], 3
	s_add_u32 s2, s0, s2
	s_addc_u32 s3, s1, s3
	s_load_dwordx2 s[2:3], s[2:3], 0xc8
	s_lshl_b32 s18, s40, 6
	s_lshl_b64 s[4:5], s[18:19], 2
	v_readlane_b32 s6, v255, 26
	v_readlane_b32 s7, v255, 27
	s_waitcnt lgkmcnt(0)
	s_add_u32 s2, s2, s4
	s_addc_u32 s3, s3, s5
	s_add_u32 s8, s2, 0x2e804000
	s_addc_u32 s9, s3, 0
	s_add_i32 s18, s40, 1
	s_mul_hi_u32 s2, s18, 0xaaaaaaab
	s_lshr_b32 s2, s2, 1
	s_mul_i32 s2, s2, 3
	s_sub_i32 s4, s18, s2
	s_and_b64 s[2:3], s[6:7], exec
	s_cselect_b32 s4, 0, s4
	s_cmp_eq_u32 s4, 2
	s_cselect_b64 s[10:11], -1, 0
	s_and_b64 s[2:3], s[10:11], exec
	s_movk_i32 s2, 0x2900
	s_cselect_b32 s5, s2, 0x2100
	s_cmp_eq_u32 s4, 1
	s_cselect_b64 s[12:13], -1, 0
	s_and_b64 s[2:3], s[12:13], exec
	v_lshlrev_b32_e32 v0, 2, v252
	s_cselect_b32 s4, 0x3100, s5
	s_and_b64 s[2:3], s[6:7], exec
	v_and_b32_e32 v70, 60, v0
	v_lshlrev_b32_e32 v0, 3, v252
	s_mul_i32 s3, s46, 0x4100
	v_bfe_u32 v78, v252, 3, 3
	v_and_b32_e32 v72, 56, v0
	s_cselect_b32 s2, 0xb00, s4
	s_add_i32 s3, s3, 0
	v_bfe_u32 v68, v252, 4, 2
	v_mul_u32_u24_e32 v0, 0x104, v72
	v_lshlrev_b32_e32 v1, 2, v78
	s_movk_i32 s6, 0x104
	v_add3_u32 v79, s3, v0, v1
	v_or_b32_e32 v0, 4, v68
	v_mov_b32_e32 v1, 0x410
	v_mad_u32_u24 v88, v0, s6, v1
	v_mov_b32_e32 v1, 0xc30
	v_lshl_add_u32 v71, v70, 2, s3
	v_mad_u32_u24 v89, v0, s6, v1
	v_mov_b32_e32 v1, 0x1450
	v_cmp_eq_u32_e64 s[4:5], 0, v252
	v_mad_u32_u24 v73, v68, s6, v71
	v_or_b32_e32 v80, 8, v78
	v_or_b32_e32 v81, 16, v78
	v_or_b32_e32 v82, 24, v78
	v_or_b32_e32 v83, 32, v78
	v_or_b32_e32 v84, 40, v78
	v_or_b32_e32 v85, 48, v78
	v_or_b32_e32 v86, 56, v78
	s_lshl_b64 s[14:15], s[18:19], 13
	v_mul_u32_u24_e32 v87, 0x104, v0
	v_mad_u32_u24 v90, v0, s6, v1
	s_mul_hi_u32 s23, s18, 0x2c00000
	s_mul_i32 s24, s18, 0x2c00000
	s_mul_hi_u32 s25, s18, 0x5800000
	s_mul_i32 s18, s18, 0x5800000
	v_mov_b32_e32 v69, v97
	s_and_saveexec_b64 s[6:7], s[4:5]
	v_mov_b32_e32 v240, 16
	s_nop 0
	global_atomic_add v240, v97, v240, s[8:9] sc0
	s_or_b64 exec, exec, s[6:7]
	s_branch .LBB0_1124

; __device__ __forceinline__ void convert_layer(int lc, unsigned* ctr, LAS unsigned char* lds, int tid, int wid, int lane) {
;     ...
;     for (;;) {
;         if (tid == 0) *slot = __hip_atomic_fetch_add(ctr, 16u, __ATOMIC_RELAXED, __HIP_MEMORY_SCOPE_AGENT);
;         __syncthreads();
;         const int base = (int)*slot;
;         __syncthreads();
;         if (base >= total) break;
.LBB0_1124:
	s_and_saveexec_b64 s[6:7], s[4:5]
	s_cbranch_execz .LBB0_1128
	s_waitcnt vmcnt(0)
	v_mov_b32_e32 v0, v240
	v_mov_b32_e32 v240, 16
	v_mov_b32_e32 v1, s44
	global_atomic_add v240, v97, v240, s[8:9] sc0
	ds_write_b32 v1, v0
.LBB0_1128:
	s_or_b64 exec, exec, s[6:7]
	v_mov_b32_e32 v0, s44
	s_waitcnt lgkmcnt(0)
	s_barrier
	ds_read_b32 v0, v0
	s_mov_b64 s[6:7], -1
	s_waitcnt lgkmcnt(0)
	s_barrier
	v_cmp_le_i32_e32 vcc, s2, v0
	v_readfirstlane_b32 s26, v0
	s_cbranch_vccnz .LBB0_1123
	s_add_i32 s26, s26, s46
	s_mov_b32 s3, 0
	s_mov_b64 s[34:35], -1
	s_branch .LBB0_1132

; __device__ __forceinline__ unsigned pk2(float lo, float hi) { f32x2 v = {lo, hi}; bf16x2_t b = __builtin_convertvector(v, bf16x2_t); return __builtin_bit_cast(unsigned, b); }
; __device__ __forceinline__ float fast_sigmoid(float g) { return __builtin_amdgcn_rcpf(1.0f + __expf(-g)); }
; __device__ __forceinline__ void convfix_phase(const float* __restrict__ halo, const float* __restrict__ cw, const float* __restrict__ cb, bf16_t* __restrict__ act, int gtid, int ngt) {
;     ...
;         const f32x4 cv = *(const f32x4*)(cb + f) + *(const f32x4*)(cw + f) * v2 + *(const f32x4*)(cw + DFF2 + f) * v1 + *(const f32x4*)(cw + 2 * DFF2 + f) * v0;
;         const f32x4 cg = *(const f32x4*)(cb + DFF + f) + *(const f32x4*)(cw + DFF + f) * g2 + *(const f32x4*)(cw + DFF2 + DFF + f) * g1 + *(const f32x4*)(cw + 2 * DFF2 + DFF + f) * g0;
;         u32x2 w; w.x = pk2(cg[0] * fast_sigmoid(cg[0]) * cv[0], cg[1] * fast_sigmoid(cg[1]) * cv[1]); w.y = pk2(cg[2] * fast_sigmoid(cg[2]) * cv[2], cg[3] * fast_sigmoid(cg[3]) * cv[3]);
;         *(u32x2*)(act + (size_t)(c * 128 + r) * DFF + f) = w;
.LBB0_1281:
	s_or_b64 exec, exec, s[56:57]
	v_ashrrev_i32_e32 v25, 31, v24
	v_lshlrev_b64 v[26:27], 2, v[24:25]
	v_lshl_add_u64 v[34:35], s[12:13], 0, v[26:27]
	v_lshl_add_u64 v[38:39], s[10:11], 0, v[26:27]
	v_lshl_add_u64 v[44:45], s[16:17], 0, v[26:27]
	v_lshl_add_u64 v[48:49], s[34:35], 0, v[26:27]
	v_lshl_add_u64 v[52:53], s[52:53], 0, v[26:27]
	v_lshl_add_u64 v[56:57], s[54:55], 0, v[26:27]
	v_lshl_add_u64 v[60:61], s[58:59], 0, v[26:27]
	v_lshl_add_u64 v[64:65], s[60:61], 0, v[26:27]
	global_load_dwordx4 v[34:37], v[34:35], off
	global_load_dwordx4 v[38:41], v[38:39], off
	global_load_dwordx4 v[44:47], v[44:45], off
	global_load_dwordx4 v[48:51], v[48:49], off
	global_load_dwordx4 v[52:55], v[52:53], off
	global_load_dwordx4 v[56:59], v[56:57], off
	global_load_dwordx4 v[60:63], v[60:61], off
	global_load_dwordx4 v[64:67], v[64:65], off
	s_movk_i32 s4, 0x2c00
	v_add_u32_e32 v28, s90, v28
	v_add_u32_e32 v29, s2, v29
	v_add_u32_e32 v30, s3, v30
	s_waitcnt vmcnt(0)
	v_pk_fma_f32 v[34:35], v[20:21], v[38:39], v[34:35]
	v_pk_fma_f32 v[36:37], v[22:23], v[40:41], v[36:37]
	v_pk_fma_f32 v[20:21], v[16:17], v[44:45], v[34:35]
	v_pk_fma_f32 v[22:23], v[18:19], v[46:47], v[36:37]
	v_pk_fma_f32 v[20:21], v[8:9], v[48:49], v[20:21]
	v_pk_fma_f32 v[22:23], v[10:11], v[50:51], v[22:23]
	v_pk_fma_f32 v[12:13], v[12:13], v[56:57], v[52:53]
	v_pk_fma_f32 v[14:15], v[14:15], v[58:59], v[54:55]
	v_pk_fma_f32 v[8:9], v[4:5], v[60:61], v[12:13]
	v_pk_fma_f32 v[10:11], v[6:7], v[62:63], v[14:15]
	v_pk_fma_f32 v[0:1], v[0:1], v[64:65], v[8:9]
	s_nop 0
	v_mul_f32_e32 v4, 0xbfb8aa3b, v0
	v_mul_f32_e32 v5, 0xbfb8aa3b, v1
	v_exp_f32_e32 v4, v4
	v_exp_f32_e32 v5, v5
	v_pk_fma_f32 v[2:3], v[2:3], v[66:67], v[10:11]
	v_add_f32_e32 v4, 1.0, v4
	v_add_f32_e32 v5, 1.0, v5
	v_rcp_f32_e32 v4, v4
	v_rcp_f32_e32 v5, v5
	s_nop 0
	v_pk_mul_f32 v[0:1], v[0:1], v[4:5]
	s_nop 0
	v_pk_mul_f32 v[0:1], v[20:21], v[0:1]
	s_nop 0
	v_cvt_pk_bf16_f32 v0, v0, v1
	v_mul_f32_e32 v1, 0xbfb8aa3b, v2
	v_exp_f32_e32 v1, v1
	s_nop 0
	v_add_f32_e32 v1, 1.0, v1
	v_rcp_f32_e32 v4, v1
	v_mul_f32_e32 v1, 0xbfb8aa3b, v3
	v_exp_f32_e32 v1, v1
	s_nop 0
	v_add_f32_e32 v1, 1.0, v1
	v_rcp_f32_e32 v5, v1
	s_nop 0
	v_pk_mul_f32 v[2:3], v[2:3], v[4:5]
	s_nop 0
	v_pk_mul_f32 v[2:3], v[22:23], v[2:3]
	v_lshl_or_b32 v4, v31, 7, v32
	v_cvt_pk_bf16_f32 v1, v2, v3
	v_mov_b64_e32 v[2:3], s[14:15]
	v_mad_i64_i32 v[2:3], s[4:5], v4, s4, v[2:3]
	s_mov_b32 s4, 0x2bfff
	s_nop 0
	v_cmp_lt_i32_e32 vcc, s4, v28
	v_lshl_add_u64 v[2:3], v[24:25], 1, v[2:3]
	s_or_b64 s[62:63], vcc, s[62:63]
	global_store_dwordx2 v[2:3], v[0:1], off
	s_andn2_b64 exec, exec, s[62:63]
	s_cbranch_execz .LBB0_1289

; __device__ __forceinline__ void convfix_phase(const float* __restrict__ halo, const float* __restrict__ cw, const float* __restrict__ cb, bf16_t* __restrict__ act, int gtid, int ngt) {
;     ...
;         const f32x4 v0 = *(const f32x4*)(hc + (size_t)r * DFF2), g0 = *(const f32x4*)(hc + (size_t)r * DFF2 + 128);
;         f32x4 v1, g1, v2, g2;
;         if (r == 1) { v1 = *(const f32x4*)(hc); g1 = *(const f32x4*)(hc + 128); if (first) { v2 = z; g2 = z; } else { v2 = *(const f32x4*)(hp + (size_t)3 * DFF2); g2 = *(const f32x4*)(hp + (size_t)3 * DFF2 + 128); } }
;         else if (first) { v1 = z; g1 = z; v2 = z; g2 = z; }
;         else { v1 = *(const f32x4*)(hp + (size_t)3 * DFF2); g1 = *(const f32x4*)(hp + (size_t)3 * DFF2 + 128); v2 = *(const f32x4*)(hp + (size_t)2 * DFF2); g2 = *(const f32x4*)(hp + (size_t)2 * DFF2 + 128); }
.LBB0_1286:
	s_andn2_saveexec_b64 s[56:57], s[56:57]
	s_cbranch_execz .LBB0_1281
	v_mov_b32_e32 v19, 0
	v_mov_b32_e32 v18, 0
	v_mov_b32_e32 v17, 0
	v_mov_b32_e32 v16, 0
	v_mov_b32_e32 v15, 0
	v_mov_b32_e32 v14, 0
	v_mov_b32_e32 v13, 0
	v_mov_b32_e32 v12, 0
	v_mov_b32_e32 v23, 0
	v_mov_b32_e32 v22, 0
	v_mov_b32_e32 v21, 0
	v_mov_b32_e32 v20, 0
	v_mov_b32_e32 v7, 0
	v_mov_b32_e32 v6, 0
	v_mov_b32_e32 v5, 0
	v_mov_b32_e32 v4, 0
	s_and_saveexec_b64 s[64:65], s[4:5]
	s_cbranch_execz .LBB0_1280
	v_add_co_u32_e32 v4, vcc, 0xffff5000, v26
	s_nop 1
	v_addc_co_u32_e32 v5, vcc, -1, v27, vcc
	v_add_co_u32_e32 v6, vcc, 0xffff6000, v26
	s_nop 1
	v_addc_co_u32_e32 v7, vcc, -1, v27, vcc
	v_add_co_u32_e32 v12, vcc, 0xfffea000, v26
	global_load_dwordx4 v[16:19], v[4:5], off
	s_nop 0
	global_load_dwordx4 v[4:7], v[6:7], off offset:-3584
	v_addc_co_u32_e32 v13, vcc, -1, v27, vcc
	v_add_co_u32_e32 v14, vcc, 0xfffeb000, v26
	s_nop 1
	v_addc_co_u32_e32 v15, vcc, -1, v27, vcc
	global_load_dwordx4 v[20:23], v[12:13], off
	s_nop 0
	global_load_dwordx4 v[12:15], v[14:15], off offset:-3584
	s_branch .LBB0_1280
